# Up GEMM K-loop: back-edge rotation (loop-carried SALU pointer/select block moved ahead of the closing barrier)
# speedup vs baseline: 1.0004x; 1.0004x over previous
.LBB0_2347:
	s_ashr_i32 s15, s14, 31
	s_lshl_b64 s[16:17], s[14:15], 19
	s_add_u32 s16, s22, s16
	s_addc_u32 s17, s23, s17
	s_and_b64 s[18:19], s[4:5], exec
	s_cselect_b32 s7, s17, s3
	s_cselect_b32 s15, s16, s2
	s_ashr_i32 s13, s12, 31
	s_lshl_b64 s[18:19], s[12:13], 19
	s_add_u32 s18, s24, s18
	s_addc_u32 s19, s25, s19
	s_and_b64 s[46:47], s[4:5], exec
	s_cselect_b32 s13, s19, s1
	s_cselect_b32 s50, s18, s0
	s_add_u32 s46, s2, 0x40080
	s_addc_u32 s47, s3, 0
	s_add_u32 s51, s0, 0x100
	v_mov_b32_e32 v4, 0
	s_addc_u32 s62, s1, 0
	s_mov_b32 s71, -2
	v_mov_b32_e32 v5, v4
	v_mov_b32_e32 v6, v4
	v_mov_b32_e32 v7, v4
	v_mov_b32_e32 v8, v4
	v_mov_b32_e32 v9, v4
	v_mov_b32_e32 v10, v4
	v_mov_b32_e32 v11, v4
	v_mov_b32_e32 v20, v4
	v_mov_b32_e32 v21, v4
	v_mov_b32_e32 v22, v4
	v_mov_b32_e32 v23, v4
	v_mov_b32_e32 v24, v4
	v_mov_b32_e32 v25, v4
	v_mov_b32_e32 v26, v4
	v_mov_b32_e32 v27, v4
	v_mov_b32_e32 v36, v4
	v_mov_b32_e32 v37, v4
	v_mov_b32_e32 v38, v4
	v_mov_b32_e32 v39, v4
	v_mov_b32_e32 v40, v4
	v_mov_b32_e32 v41, v4
	v_mov_b32_e32 v42, v4
	v_mov_b32_e32 v43, v4
	s_waitcnt vmcnt(0)
	v_mov_b32_e32 v52, v4
	v_mov_b32_e32 v53, v4
	v_mov_b32_e32 v54, v4
	v_mov_b32_e32 v55, v4
	v_mov_b32_e32 v56, v4
	v_mov_b32_e32 v57, v4
	v_mov_b32_e32 v58, v4
	v_mov_b32_e32 v59, v4
	v_mov_b32_e32 v12, v4
	v_mov_b32_e32 v13, v4
	v_mov_b32_e32 v14, v4
	v_mov_b32_e32 v15, v4
	v_mov_b32_e32 v16, v4
	v_mov_b32_e32 v17, v4
	v_mov_b32_e32 v18, v4
	v_mov_b32_e32 v19, v4
	v_mov_b32_e32 v28, v4
	v_mov_b32_e32 v29, v4
	v_mov_b32_e32 v30, v4
	v_mov_b32_e32 v31, v4
	v_mov_b32_e32 v32, v4
	v_mov_b32_e32 v33, v4
	v_mov_b32_e32 v34, v4
	v_mov_b32_e32 v35, v4
	v_mov_b32_e32 v44, v4
	v_mov_b32_e32 v45, v4
	v_mov_b32_e32 v46, v4
	v_mov_b32_e32 v47, v4
	v_mov_b32_e32 v48, v4
	v_mov_b32_e32 v49, v4
	v_mov_b32_e32 v50, v4
	v_mov_b32_e32 v51, v4
	v_mov_b32_e32 v60, v4
	v_mov_b32_e32 v61, v4
	v_mov_b32_e32 v62, v4
	v_mov_b32_e32 v63, v4
	v_mov_b32_e32 v64, v4
	v_mov_b32_e32 v65, v4
	v_mov_b32_e32 v66, v4
	v_mov_b32_e32 v67, v4
	v_mov_b32_e32 v68, v4
	v_mov_b32_e32 v69, v4
	v_mov_b32_e32 v70, v4
	v_mov_b32_e32 v71, v4
	v_mov_b32_e32 v72, v4
	v_mov_b32_e32 v73, v4
	v_mov_b32_e32 v74, v4
	v_mov_b32_e32 v75, v4
	v_mov_b32_e32 v84, v4
	v_mov_b32_e32 v85, v4
	v_mov_b32_e32 v86, v4
	v_mov_b32_e32 v87, v4
	v_mov_b32_e32 v88, v4
	v_mov_b32_e32 v89, v4
	v_mov_b32_e32 v90, v4
	v_mov_b32_e32 v91, v4
	v_mov_b32_e32 v100, v4
	v_mov_b32_e32 v101, v4
	v_mov_b32_e32 v102, v4
	v_mov_b32_e32 v103, v4
	v_mov_b32_e32 v104, v4
	v_mov_b32_e32 v105, v4
	v_mov_b32_e32 v106, v4
	v_mov_b32_e32 v107, v4
	v_mov_b32_e32 v116, v4
	v_mov_b32_e32 v117, v4
	v_mov_b32_e32 v118, v4
	v_mov_b32_e32 v119, v4
	v_mov_b32_e32 v120, v4
	v_mov_b32_e32 v121, v4
	v_mov_b32_e32 v122, v4
	v_mov_b32_e32 v123, v4
	v_mov_b32_e32 v76, v4
	v_mov_b32_e32 v77, v4
	v_mov_b32_e32 v78, v4
	v_mov_b32_e32 v79, v4
	v_mov_b32_e32 v80, v4
	v_mov_b32_e32 v81, v4
	v_mov_b32_e32 v82, v4
	v_mov_b32_e32 v83, v4
	v_mov_b32_e32 v92, v4
	v_mov_b32_e32 v93, v4
	v_mov_b32_e32 v94, v4
	v_mov_b32_e32 v95, v4
	v_mov_b32_e32 v96, v4
	v_mov_b32_e32 v97, v4
	v_mov_b32_e32 v98, v4
	v_mov_b32_e32 v99, v4
	v_mov_b32_e32 v108, v4
	v_mov_b32_e32 v109, v4
	v_mov_b32_e32 v110, v4
	v_mov_b32_e32 v111, v4
	v_mov_b32_e32 v112, v4
	v_mov_b32_e32 v113, v4
	v_mov_b32_e32 v114, v4
	v_mov_b32_e32 v115, v4
	v_mov_b32_e32 v124, v4
	v_mov_b32_e32 v125, v4
	v_mov_b32_e32 v126, v4
	v_mov_b32_e32 v127, v4
	v_mov_b32_e32 v128, v4
	v_mov_b32_e32 v129, v4
	v_mov_b32_e32 v130, v4
	v_mov_b32_e32 v131, v4
	s_add_u32 s0, s46, 0xfffc0080
	s_addc_u32 s1, s47, -1
	s_add_i32 s64, 0, 0x10000
	s_cmp_eq_u32 s71, 12
	s_cselect_b32 s3, s7, s1
	s_cselect_b32 s2, s15, s0
	s_cselect_b32 s1, s13, s62
	s_cselect_b32 s0, s50, s51
	s_add_i32 s76, 0, 0x14000
.LBB0_2348:
	v_add_u32_e32 v144, s64, v3
	v_add_u32_e32 v167, s76, v3
	ds_read_b128 v[132:135], v144
	ds_read_b128 v[136:139], v144 offset:1024
	ds_read_b128 v[140:143], v144 offset:2048
	ds_read_b128 v[144:147], v144 offset:3072
	ds_read_b128 v[158:161], v167
	ds_read_b128 v[162:165], v167 offset:1024
	ds_read_b128 v[168:171], v167 offset:2048
	ds_read_b128 v[172:175], v167 offset:3072
	v_lshl_add_u64 v[208:209], s[46:47], 0, v[154:155]
	s_add_i32 m0, s21, 0xc000
	ds_read_b128 v[176:179], v166
	ds_read_b128 v[180:183], v166 offset:1024
	ds_read_b128 v[184:187], v166 offset:2048
	ds_read_b128 v[188:191], v166 offset:3072
	ds_read_b128 v[192:195], v166 offset:4096
	ds_read_b128 v[196:199], v166 offset:5120
	ds_read_b128 v[200:203], v166 offset:6144
	ds_read_b128 v[204:207], v166 offset:7168
	global_load_lds_dwordx4 v[208:209], off
	v_lshl_add_u64 v[208:209], s[46:47], 0, v[156:157]
	s_add_i32 m0, s21, 0xe000
	s_nop 0
	global_load_lds_dwordx4 v[208:209], off
	s_waitcnt vmcnt(8)
	s_waitcnt lgkmcnt(0)
	s_barrier
	s_setprio 1
	s_waitcnt lgkmcnt(0)
	v_mfma_f32_16x16x32_bf16 v[128:131], v[132:135], v[176:179], v[128:131]
	v_mfma_f32_16x16x32_bf16 v[124:127], v[140:143], v[176:179], v[124:127]
	v_mfma_f32_16x16x32_bf16 v[112:115], v[132:135], v[184:187], v[112:115]
	v_mfma_f32_16x16x32_bf16 v[108:111], v[140:143], v[184:187], v[108:111]
	v_mfma_f32_16x16x32_bf16 v[96:99], v[132:135], v[192:195], v[96:99]
	v_mfma_f32_16x16x32_bf16 v[92:95], v[140:143], v[192:195], v[92:95]
	v_mfma_f32_16x16x32_bf16 v[80:83], v[132:135], v[200:203], v[80:83]
	v_mfma_f32_16x16x32_bf16 v[76:79], v[140:143], v[200:203], v[76:79]
	v_mfma_f32_16x16x32_bf16 v[128:131], v[136:139], v[180:183], v[128:131]
	v_mfma_f32_16x16x32_bf16 v[124:127], v[144:147], v[180:183], v[124:127]
	v_mfma_f32_16x16x32_bf16 v[112:115], v[136:139], v[188:191], v[112:115]
	v_mfma_f32_16x16x32_bf16 v[108:111], v[144:147], v[188:191], v[108:111]
	v_mfma_f32_16x16x32_bf16 v[96:99], v[136:139], v[196:199], v[96:99]
	v_mfma_f32_16x16x32_bf16 v[92:95], v[144:147], v[196:199], v[92:95]
	v_mfma_f32_16x16x32_bf16 v[80:83], v[136:139], v[204:207], v[80:83]
	v_mfma_f32_16x16x32_bf16 v[76:79], v[144:147], v[204:207], v[76:79]
	s_setprio 0
	s_setprio 1
	v_mfma_f32_16x16x32_bf16 v[120:123], v[158:161], v[176:179], v[120:123]
	v_mfma_f32_16x16x32_bf16 v[116:119], v[168:171], v[176:179], v[116:119]
	v_mfma_f32_16x16x32_bf16 v[104:107], v[158:161], v[184:187], v[104:107]
	v_mfma_f32_16x16x32_bf16 v[100:103], v[168:171], v[184:187], v[100:103]
	v_mfma_f32_16x16x32_bf16 v[88:91], v[158:161], v[192:195], v[88:91]
	v_mfma_f32_16x16x32_bf16 v[84:87], v[168:171], v[192:195], v[84:87]
	v_mfma_f32_16x16x32_bf16 v[72:75], v[158:161], v[200:203], v[72:75]
	v_mfma_f32_16x16x32_bf16 v[68:71], v[168:171], v[200:203], v[68:71]
	v_mfma_f32_16x16x32_bf16 v[120:123], v[162:165], v[180:183], v[120:123]
	v_mfma_f32_16x16x32_bf16 v[116:119], v[172:175], v[180:183], v[116:119]
	v_mfma_f32_16x16x32_bf16 v[104:107], v[162:165], v[188:191], v[104:107]
	v_mfma_f32_16x16x32_bf16 v[100:103], v[172:175], v[188:191], v[100:103]
	v_mfma_f32_16x16x32_bf16 v[88:91], v[162:165], v[196:199], v[88:91]
	v_mfma_f32_16x16x32_bf16 v[84:87], v[172:175], v[196:199], v[84:87]
	v_mfma_f32_16x16x32_bf16 v[72:75], v[162:165], v[204:207], v[72:75]
	v_mfma_f32_16x16x32_bf16 v[68:71], v[172:175], v[204:207], v[68:71]
	s_setprio 0
	s_barrier
	s_add_i32 s64, s64, s29
	v_lshl_add_u64 v[208:209], s[0:1], 0, v[148:149]
	s_mov_b32 m0, s64
	ds_read_b128 v[176:179], v166 offset:16384
	ds_read_b128 v[180:183], v166 offset:17408
	ds_read_b128 v[184:187], v166 offset:18432
	ds_read_b128 v[188:191], v166 offset:19456
	ds_read_b128 v[192:195], v166 offset:20480
	ds_read_b128 v[196:199], v166 offset:21504
	ds_read_b128 v[200:203], v166 offset:22528
	ds_read_b128 v[204:207], v166 offset:23552
	global_load_lds_dwordx4 v[208:209], off
	s_add_i32 m0, s64, 0x2000
	s_add_u32 s64, s0, 0x4000
	v_lshl_add_u64 v[210:211], s[0:1], 0, v[152:153]
	s_addc_u32 s65, s1, 0
	s_add_i32 s76, s76, s29
	global_load_lds_dwordx4 v[210:211], off
	v_lshl_add_u64 v[212:213], s[64:65], 0, v[148:149]
	s_mov_b32 m0, s76
	v_lshl_add_u64 v[214:215], s[2:3], 0, v[150:151]
	global_load_lds_dwordx4 v[212:213], off
	v_lshl_add_u64 v[212:213], s[64:65], 0, v[152:153]
	s_add_i32 m0, s76, 0x2000
	s_nop 0
	global_load_lds_dwordx4 v[212:213], off
	v_lshl_add_u64 v[212:213], s[2:3], 0, v[0:1]
	s_mov_b32 m0, s21
	s_nop 0
	global_load_lds_dwordx4 v[212:213], off
	s_mov_b32 m0, s30
	s_nop 0
	global_load_lds_dwordx4 v[214:215], off
	s_waitcnt vmcnt(8)
	s_waitcnt lgkmcnt(0)
	s_barrier
	s_setprio 1
	s_waitcnt lgkmcnt(0)
	v_mfma_f32_16x16x32_bf16 v[64:67], v[132:135], v[176:179], v[64:67]
	v_mfma_f32_16x16x32_bf16 v[60:63], v[140:143], v[176:179], v[60:63]
	v_mfma_f32_16x16x32_bf16 v[48:51], v[132:135], v[184:187], v[48:51]
	v_mfma_f32_16x16x32_bf16 v[44:47], v[140:143], v[184:187], v[44:47]
	v_mfma_f32_16x16x32_bf16 v[32:35], v[132:135], v[192:195], v[32:35]
	v_mfma_f32_16x16x32_bf16 v[28:31], v[140:143], v[192:195], v[28:31]
	v_mfma_f32_16x16x32_bf16 v[16:19], v[132:135], v[200:203], v[16:19]
	v_mfma_f32_16x16x32_bf16 v[12:15], v[140:143], v[200:203], v[12:15]
	v_mfma_f32_16x16x32_bf16 v[64:67], v[136:139], v[180:183], v[64:67]
	v_mfma_f32_16x16x32_bf16 v[60:63], v[144:147], v[180:183], v[60:63]
	v_mfma_f32_16x16x32_bf16 v[48:51], v[136:139], v[188:191], v[48:51]
	v_mfma_f32_16x16x32_bf16 v[44:47], v[144:147], v[188:191], v[44:47]
	v_mfma_f32_16x16x32_bf16 v[32:35], v[136:139], v[196:199], v[32:35]
	v_mfma_f32_16x16x32_bf16 v[28:31], v[144:147], v[196:199], v[28:31]
	v_mfma_f32_16x16x32_bf16 v[16:19], v[136:139], v[204:207], v[16:19]
	v_mfma_f32_16x16x32_bf16 v[12:15], v[144:147], v[204:207], v[12:15]
	s_setprio 0
	s_setprio 1
	v_mfma_f32_16x16x32_bf16 v[56:59], v[158:161], v[176:179], v[56:59]
	v_mfma_f32_16x16x32_bf16 v[52:55], v[168:171], v[176:179], v[52:55]
	v_mfma_f32_16x16x32_bf16 v[40:43], v[158:161], v[184:187], v[40:43]
	v_mfma_f32_16x16x32_bf16 v[36:39], v[168:171], v[184:187], v[36:39]
	v_mfma_f32_16x16x32_bf16 v[24:27], v[158:161], v[192:195], v[24:27]
	v_mfma_f32_16x16x32_bf16 v[20:23], v[168:171], v[192:195], v[20:23]
	v_mfma_f32_16x16x32_bf16 v[8:11], v[158:161], v[200:203], v[8:11]
	v_mfma_f32_16x16x32_bf16 v[4:7], v[168:171], v[200:203], v[4:7]
	v_mfma_f32_16x16x32_bf16 v[56:59], v[162:165], v[180:183], v[56:59]
	v_mfma_f32_16x16x32_bf16 v[52:55], v[172:175], v[180:183], v[52:55]
	v_mfma_f32_16x16x32_bf16 v[40:43], v[162:165], v[188:191], v[40:43]
	v_mfma_f32_16x16x32_bf16 v[36:39], v[172:175], v[188:191], v[36:39]
	v_mfma_f32_16x16x32_bf16 v[24:27], v[162:165], v[196:199], v[24:27]
	v_mfma_f32_16x16x32_bf16 v[20:23], v[172:175], v[196:199], v[20:23]
	v_mfma_f32_16x16x32_bf16 v[8:11], v[162:165], v[204:207], v[8:11]
	v_mfma_f32_16x16x32_bf16 v[4:7], v[172:175], v[204:207], v[4:7]
	s_setprio 0
	s_barrier
	s_add_i32 s64, 0, 0x18000
	s_add_i32 s65, 0, 0x1c000
	v_add_u32_e32 v144, s64, v3
	v_add_u32_e32 v167, s65, v3
	ds_read_b128 v[132:135], v144
	ds_read_b128 v[136:139], v144 offset:1024
	ds_read_b128 v[140:143], v144 offset:2048
	ds_read_b128 v[144:147], v144 offset:3072
	ds_read_b128 v[158:161], v167
	ds_read_b128 v[162:165], v167 offset:1024
	ds_read_b128 v[168:171], v167 offset:2048
	ds_read_b128 v[172:175], v167 offset:3072
	s_add_u32 s2, s2, 0x40000
	s_addc_u32 s3, s3, 0
	s_mov_b32 m0, s31
	v_lshl_add_u64 v[216:217], s[2:3], 0, v[0:1]
	ds_read_b128 v[176:179], v166 offset:32768
	ds_read_b128 v[180:183], v166 offset:33792
	ds_read_b128 v[184:187], v166 offset:34816
	ds_read_b128 v[188:191], v166 offset:35840
	ds_read_b128 v[192:195], v166 offset:36864
	ds_read_b128 v[196:199], v166 offset:37888
	ds_read_b128 v[200:203], v166 offset:38912
	ds_read_b128 v[204:207], v166 offset:39936
	global_load_lds_dwordx4 v[216:217], off
	v_lshl_add_u64 v[216:217], s[2:3], 0, v[150:151]
	s_mov_b32 m0, s52
	s_nop 0
	global_load_lds_dwordx4 v[216:217], off
	s_waitcnt vmcnt(8)
	s_waitcnt lgkmcnt(0)
	s_barrier
	s_setprio 1
	s_waitcnt lgkmcnt(0)
	v_mfma_f32_16x16x32_bf16 v[128:131], v[132:135], v[176:179], v[128:131]
	v_mfma_f32_16x16x32_bf16 v[124:127], v[140:143], v[176:179], v[124:127]
	v_mfma_f32_16x16x32_bf16 v[112:115], v[132:135], v[184:187], v[112:115]
	v_mfma_f32_16x16x32_bf16 v[108:111], v[140:143], v[184:187], v[108:111]
	v_mfma_f32_16x16x32_bf16 v[96:99], v[132:135], v[192:195], v[96:99]
	v_mfma_f32_16x16x32_bf16 v[92:95], v[140:143], v[192:195], v[92:95]
	v_mfma_f32_16x16x32_bf16 v[80:83], v[132:135], v[200:203], v[80:83]
	v_mfma_f32_16x16x32_bf16 v[76:79], v[140:143], v[200:203], v[76:79]
	v_mfma_f32_16x16x32_bf16 v[128:131], v[136:139], v[180:183], v[128:131]
	v_mfma_f32_16x16x32_bf16 v[124:127], v[144:147], v[180:183], v[124:127]
	v_mfma_f32_16x16x32_bf16 v[112:115], v[136:139], v[188:191], v[112:115]
	v_mfma_f32_16x16x32_bf16 v[108:111], v[144:147], v[188:191], v[108:111]
	v_mfma_f32_16x16x32_bf16 v[96:99], v[136:139], v[196:199], v[96:99]
	v_mfma_f32_16x16x32_bf16 v[92:95], v[144:147], v[196:199], v[92:95]
	v_mfma_f32_16x16x32_bf16 v[80:83], v[136:139], v[204:207], v[80:83]
	v_mfma_f32_16x16x32_bf16 v[76:79], v[144:147], v[204:207], v[76:79]
	s_setprio 0
	s_setprio 1
	v_mfma_f32_16x16x32_bf16 v[120:123], v[158:161], v[176:179], v[120:123]
	v_mfma_f32_16x16x32_bf16 v[116:119], v[168:171], v[176:179], v[116:119]
	v_mfma_f32_16x16x32_bf16 v[104:107], v[158:161], v[184:187], v[104:107]
	v_mfma_f32_16x16x32_bf16 v[100:103], v[168:171], v[184:187], v[100:103]
	v_mfma_f32_16x16x32_bf16 v[88:91], v[158:161], v[192:195], v[88:91]
	v_mfma_f32_16x16x32_bf16 v[84:87], v[168:171], v[192:195], v[84:87]
	v_mfma_f32_16x16x32_bf16 v[72:75], v[158:161], v[200:203], v[72:75]
	v_mfma_f32_16x16x32_bf16 v[68:71], v[168:171], v[200:203], v[68:71]
	v_mfma_f32_16x16x32_bf16 v[120:123], v[162:165], v[180:183], v[120:123]
	v_mfma_f32_16x16x32_bf16 v[116:119], v[172:175], v[180:183], v[116:119]
	v_mfma_f32_16x16x32_bf16 v[104:107], v[162:165], v[188:191], v[104:107]
	v_mfma_f32_16x16x32_bf16 v[100:103], v[172:175], v[188:191], v[100:103]
	v_mfma_f32_16x16x32_bf16 v[88:91], v[162:165], v[196:199], v[88:91]
	v_mfma_f32_16x16x32_bf16 v[84:87], v[172:175], v[196:199], v[84:87]
	v_mfma_f32_16x16x32_bf16 v[72:75], v[162:165], v[204:207], v[72:75]
	v_mfma_f32_16x16x32_bf16 v[68:71], v[172:175], v[204:207], v[68:71]
	s_setprio 0
	s_barrier
	s_add_i32 s2, s64, s29
	v_lshl_add_u64 v[208:209], v[208:209], 0, s[60:61]
	s_mov_b32 m0, s2
	ds_read_b128 v[176:179], v166 offset:49152
	ds_read_b128 v[180:183], v166 offset:50176
	ds_read_b128 v[184:187], v166 offset:51200
	ds_read_b128 v[188:191], v166 offset:52224
	ds_read_b128 v[192:195], v166 offset:53248
	ds_read_b128 v[196:199], v166 offset:54272
	ds_read_b128 v[200:203], v166 offset:55296
	ds_read_b128 v[204:207], v166 offset:56320
	global_load_lds_dwordx4 v[208:209], off
	s_add_i32 m0, s2, 0x2000
	s_add_u32 s0, s0, 0x4080
	v_lshl_add_u64 v[208:209], v[210:211], 0, s[60:61]
	s_addc_u32 s1, s1, 0
	s_add_i32 s2, s65, s29
	global_load_lds_dwordx4 v[208:209], off
	v_lshl_add_u64 v[208:209], s[0:1], 0, v[148:149]
	s_mov_b32 m0, s2
	s_nop 0
	global_load_lds_dwordx4 v[208:209], off
	v_lshl_add_u64 v[208:209], s[0:1], 0, v[152:153]
	s_add_i32 m0, s2, 0x2000
	s_nop 0
	global_load_lds_dwordx4 v[208:209], off
	v_lshl_add_u64 v[208:209], v[212:213], 0, s[60:61]
	s_mov_b32 m0, s56
	s_nop 0
	global_load_lds_dwordx4 v[208:209], off
	v_lshl_add_u64 v[208:209], v[214:215], 0, s[60:61]
	s_mov_b32 m0, s57
	s_nop 0
	global_load_lds_dwordx4 v[208:209], off
	s_waitcnt vmcnt(8)
	s_waitcnt lgkmcnt(0)
	s_barrier
	s_setprio 1
	s_waitcnt lgkmcnt(0)
	v_mfma_f32_16x16x32_bf16 v[64:67], v[132:135], v[176:179], v[64:67]
	v_mfma_f32_16x16x32_bf16 v[60:63], v[140:143], v[176:179], v[60:63]
	v_mfma_f32_16x16x32_bf16 v[48:51], v[132:135], v[184:187], v[48:51]
	v_mfma_f32_16x16x32_bf16 v[44:47], v[140:143], v[184:187], v[44:47]
	v_mfma_f32_16x16x32_bf16 v[32:35], v[132:135], v[192:195], v[32:35]
	v_mfma_f32_16x16x32_bf16 v[28:31], v[140:143], v[192:195], v[28:31]
	v_mfma_f32_16x16x32_bf16 v[16:19], v[132:135], v[200:203], v[16:19]
	v_mfma_f32_16x16x32_bf16 v[12:15], v[140:143], v[200:203], v[12:15]
	v_mfma_f32_16x16x32_bf16 v[64:67], v[136:139], v[180:183], v[64:67]
	v_mfma_f32_16x16x32_bf16 v[60:63], v[144:147], v[180:183], v[60:63]
	v_mfma_f32_16x16x32_bf16 v[48:51], v[136:139], v[188:191], v[48:51]
	v_mfma_f32_16x16x32_bf16 v[44:47], v[144:147], v[188:191], v[44:47]
	v_mfma_f32_16x16x32_bf16 v[32:35], v[136:139], v[196:199], v[32:35]
	v_mfma_f32_16x16x32_bf16 v[28:31], v[144:147], v[196:199], v[28:31]
	v_mfma_f32_16x16x32_bf16 v[16:19], v[136:139], v[204:207], v[16:19]
	v_mfma_f32_16x16x32_bf16 v[12:15], v[144:147], v[204:207], v[12:15]
	s_setprio 0
	s_setprio 1
	v_mfma_f32_16x16x32_bf16 v[56:59], v[158:161], v[176:179], v[56:59]
	v_mfma_f32_16x16x32_bf16 v[52:55], v[168:171], v[176:179], v[52:55]
	v_mfma_f32_16x16x32_bf16 v[40:43], v[158:161], v[184:187], v[40:43]
	v_mfma_f32_16x16x32_bf16 v[36:39], v[168:171], v[184:187], v[36:39]
	v_mfma_f32_16x16x32_bf16 v[24:27], v[158:161], v[192:195], v[24:27]
	v_mfma_f32_16x16x32_bf16 v[20:23], v[168:171], v[192:195], v[20:23]
	v_mfma_f32_16x16x32_bf16 v[8:11], v[158:161], v[200:203], v[8:11]
	v_mfma_f32_16x16x32_bf16 v[4:7], v[168:171], v[200:203], v[4:7]
	v_mfma_f32_16x16x32_bf16 v[56:59], v[162:165], v[180:183], v[56:59]
	v_mfma_f32_16x16x32_bf16 v[52:55], v[172:175], v[180:183], v[52:55]
	v_mfma_f32_16x16x32_bf16 v[40:43], v[162:165], v[188:191], v[40:43]
	v_mfma_f32_16x16x32_bf16 v[36:39], v[172:175], v[188:191], v[36:39]
	v_mfma_f32_16x16x32_bf16 v[24:27], v[162:165], v[196:199], v[24:27]
	v_mfma_f32_16x16x32_bf16 v[20:23], v[172:175], v[196:199], v[20:23]
	v_mfma_f32_16x16x32_bf16 v[8:11], v[162:165], v[204:207], v[8:11]
	v_mfma_f32_16x16x32_bf16 v[4:7], v[172:175], v[204:207], v[4:7]
	s_setprio 0
	s_add_i32 s71, s71, 2
	s_add_u32 s46, s46, 0x100
	s_addc_u32 s47, s47, 0
	s_add_u32 s51, s51, 0x100
	s_addc_u32 s62, s62, 0
	s_add_u32 s0, s46, 0xfffc0080
	s_addc_u32 s1, s47, -1
	s_add_i32 s64, 0, 0x10000
	s_cmp_eq_u32 s71, 12
	s_cselect_b32 s3, s7, s1
	s_cselect_b32 s2, s15, s0
	s_cselect_b32 s1, s13, s62
	s_cselect_b32 s0, s50, s51
	s_add_i32 s76, 0, 0x14000
	s_cmp_gt_u32 s71, 13
	s_barrier
	s_cbranch_scc0 .LBB0_2348
	s_and_b64 vcc, exec, s[10:11]
	s_cbranch_vccz .LBB0_2351
	s_barrier
